# scan VN step: both NakT fragment reads issued up front, the two MFMAs back to back
# speedup vs baseline: 1.0082x; 1.0082x over previous
; __device__ __forceinline__ uint2 pack4(f32x4 v) { uint2 u; u.x = cvt_pk_bf16(v[0], v[1]); u.y = cvt_pk_bf16(v[2], v[3]); return u; }
; #define MFMA16(a, b, c) __builtin_amdgcn_mfma_f32_16x16x32_bf16(a, b, c, 0, 0, 0)
; __device__ __forceinline__ void scan_phase(PREF p, char* smem, const int wid_u) {
;     ...
;       } else if (wave == 2 || wave == 3 || wave >= 6) {
;         const int vtile = wave < 4 ? wave - 2 : wave - 4;
;         const bf16x8 vf = ldfrag(VT, 40, vtile * 16, 0, fr, fq);
;         const f32x4 zero = {0.f, 0.f, 0.f, 0.f};
; #pragma unroll
;         for (int tt = 0; tt < 2; ++tt) {
;           const f32x4 acc = MFMA16(ldfrag(NakT, 40, tt * 16, 0, fr, fq), vf, zero);
;           *(uint2*)(VNb + (vtile * 16 + fr) * 40 + tt * 16 + fq * 4) = pack4(acc);
;         }
.LBB0_556:
	s_andn2_b64 vcc, exec, s[66:67]
	s_cbranch_vccnz .LBB0_558
	v_add_u32_e32 v64, v130, v165
	ds_read_b128 v[56:59], v64 offset:4096
	v_add_u32_e32 v60, v131, v136
	ds_read_b128 v[60:63], v60
	ds_read_b128 v[66:69], v64 offset:5376
	s_waitcnt lgkmcnt(1)
	v_mfma_f32_16x16x32_bf16 v[56:59], v[56:59], v[60:63], 0
	s_waitcnt lgkmcnt(0)
	v_mfma_f32_16x16x32_bf16 v[66:69], v[66:69], v[60:63], 0
	s_nop 7
	v_cvt_pk_bf16_f32 v56, v56, v57
	v_cvt_pk_bf16_f32 v57, v58, v59
	ds_write_b64 v173, v[56:57] offset:39936
	v_cvt_pk_bf16_f32 v66, v66, v67
	v_cvt_pk_bf16_f32 v67, v68, v69
	ds_write_b64 v173, v[66:67] offset:39968
